# seams: wait only for the arrive atomic before the flag decision; drop two acquire invalidates adjacent to a light-barrier invalidate; issue the P1 acquire invalidate before polling the adaLN counter
# speedup vs baseline: 1.0234x; 1.0027x over previous
.LBB0_147:
	s_or_b64 exec, exec, s[56:57]
	s_cmp_lt_u32 s74, 64
	s_cselect_b64 s[10:11], -1, 0
	s_cmp_gt_u32 s74, 63
	s_cbranch_scc1 .LBB0_160
	v_mov_b32_e32 v56, 0x28000
	s_waitcnt lgkmcnt(0)
	buffer_inv sc1
	global_load_dword v56, v56, s[8:9] sc1
	s_movk_i32 s26, 0xbf
	s_add_u32 s34, s8, 0x28000
	s_addc_u32 s35, s9, 0
	s_waitcnt vmcnt(0)
	v_cmp_lt_u32_e32 vcc, s26, v56
	s_cbranch_vccnz .LBB0_159
	s_mov_b32 s27, 0x3ffff8
	v_mov_b32_e32 v56, 0
	s_movk_i32 s58, 0xc0
	s_branch .LBB0_151

.LBB0_159:
	s_nop 0

.LBB0_218:
	s_nop 0
	s_waitcnt vmcnt(0)

.LBB0_295:
	s_or_b64 exec, exec, s[10:11]
	buffer_inv sc1
	s_waitcnt vmcnt(1)
	v_readfirstlane_b32 s3, v1
	s_add_u32 s6, s6, 0x34100
	s_addc_u32 s7, s7, 0
	v_add_u32_e32 v0, s3, v0
	v_cmp_ne_u32_e32 vcc, 31, v0
	s_and_saveexec_b64 s[8:9], vcc
	s_xor_b64 s[8:9], exec, s[8:9]
	s_cbranch_execz .LBB0_297
	v_mov_b32_e32 v0, 0
	global_load_dword v1, v0, s[6:7] sc1
	s_waitcnt vmcnt(0)
	v_cmp_ne_u32_e32 vcc, 0, v1
	s_cbranch_vccz .LBB0_611

.LBB0_633:
	s_or_b64 exec, exec, s[10:11]
	buffer_inv sc1
	s_waitcnt vmcnt(1)
	v_readfirstlane_b32 s3, v1
	s_add_u32 s6, s6, 0x33100
	s_addc_u32 s7, s7, 0
	v_add_u32_e32 v0, s3, v0
	v_cmp_ne_u32_e32 vcc, 31, v0
	s_and_saveexec_b64 s[8:9], vcc
	s_xor_b64 s[8:9], exec, s[8:9]
	s_cbranch_execz .LBB0_635
	v_mov_b32_e32 v0, 0
	global_load_dword v1, v0, s[6:7] sc1
	s_waitcnt vmcnt(0)
	v_cmp_ne_u32_e32 vcc, 0, v1
	s_cbranch_vccz .LBB0_778

.LBB0_800:
	s_or_b64 exec, exec, s[10:11]
	buffer_inv sc1
	s_waitcnt vmcnt(1)
	v_readfirstlane_b32 s3, v1
	s_add_u32 s6, s6, 0x35100
	s_addc_u32 s7, s7, 0
	v_add_u32_e32 v0, s3, v0
	v_cmp_ne_u32_e32 vcc, 31, v0
	s_and_saveexec_b64 s[8:9], vcc
	s_xor_b64 s[8:9], exec, s[8:9]
	s_cbranch_execz .LBB0_802
	v_mov_b32_e32 v0, 0
	global_load_dword v1, v0, s[6:7] sc1
	s_waitcnt vmcnt(0)
	v_cmp_ne_u32_e32 vcc, 0, v1
	s_cbranch_vccz .LBB0_889

.LBB0_911:
	s_or_b64 exec, exec, s[10:11]
	buffer_inv sc1
	s_waitcnt vmcnt(1)
	v_readfirstlane_b32 s3, v1
	s_nop 1
	v_add_u32_e32 v0, s3, v0
	v_cmp_ne_u32_e32 vcc, 31, v0
	s_and_saveexec_b64 s[8:9], vcc
	s_xor_b64 s[8:9], exec, s[8:9]
	s_cbranch_execz .LBB0_913
	v_mov_b32_e32 v0, 0
	global_load_dword v1, v0, s[6:7] offset:256 sc1
	s_waitcnt vmcnt(0)
	v_cmp_ne_u32_e32 vcc, 0, v1
	s_cbranch_vccz .LBB0_1397

.LBB0_1419:
	s_or_b64 exec, exec, s[10:11]
	buffer_inv sc1
	s_waitcnt vmcnt(1)
	v_readfirstlane_b32 s3, v1
	s_add_u32 s6, s6, 0x31100
	s_addc_u32 s7, s7, 0
	v_add_u32_e32 v0, s3, v0
	v_cmp_ne_u32_e32 vcc, 31, v0
	s_and_saveexec_b64 s[8:9], vcc
	s_xor_b64 s[8:9], exec, s[8:9]
	s_cbranch_execz .LBB0_1421
	v_mov_b32_e32 v0, 0
	global_load_dword v1, v0, s[6:7] sc1
	s_waitcnt vmcnt(0)
	v_cmp_ne_u32_e32 vcc, 0, v1
	s_cbranch_vccz .LBB0_1480

.LBB0_1502:
	s_or_b64 exec, exec, s[10:11]
	buffer_inv sc1
	s_waitcnt vmcnt(1)
	v_readfirstlane_b32 s3, v1
	s_add_u32 s6, s6, 0x32100
	s_addc_u32 s7, s7, 0
	v_add_u32_e32 v0, s3, v0
	v_cmp_ne_u32_e32 vcc, 31, v0
	s_and_saveexec_b64 s[8:9], vcc
	s_xor_b64 s[8:9], exec, s[8:9]
	s_cbranch_execz .LBB0_1504
	v_mov_b32_e32 v0, 0
	global_load_dword v1, v0, s[6:7] sc1
	s_waitcnt vmcnt(0)
	v_cmp_ne_u32_e32 vcc, 0, v1
	s_cbranch_vccz .LBB0_1527
